# RWKV D2 inter-chunk loop hand-written (SGPR-base LDS-DMA with immediates, fewer instructions) + M2 rebalance: gMLP tiles of workgroups 128-131 (which carry the sample S5 tiles) moved to 252-255
# speedup vs baseline: 1.0911x; 1.0137x over previous
.LBB0_579:
	v_readlane_b32 s38, v255, 9
	s_and_b64 vcc, exec, s[8:9]
	v_readlane_b32 s39, v255, 10
	s_cbranch_vccz .LBB0_599
	v_readlane_b32 s10, v253, 47
	v_readlane_b32 s11, v253, 48
	v_readlane_b32 s4, v254, 19
	v_readlane_b32 s5, v254, 21
	v_readlane_b32 s2, v254, 25
	v_readlane_b32 s3, v254, 26
	v_and_b32_e32 v16, 15, v10
	v_lshrrev_b32_e32 v17, 4, v10
	v_lshlrev_b32_e32 v18, 4, v10
	v_add_u32_e32 v19, 0x1000, v18
	v_add_u32_e32 v20, 0x2000, v18
	v_add_u32_e32 v21, 0x3000, v18
	v_add_u32_e32 v22, s4, v21
	v_add_u32_e32 v23, 0x3c00, v18
	v_add_u32_e32 v23, s4, v23
	v_add_u32_e32 v24, 0x5800, v18
	v_add_u32_e32 v24, s5, v24
	v_add_u32_e32 v25, 0x7000, v18
	s_add_u32 s12, s78, s2
	s_addc_u32 s13, s79, s3
	s_sub_u32 s12, s12, 0x4c00
	s_subb_u32 s13, s13, 0
	v_lshlrev_b32_e32 v26, 2, v16
	v_lshl_or_b32 v26, v17, 12, v26
	v_add_u32_e32 v27, 0x4000, v26
	v_and_b32_e32 v28, 7, v16
	v_xor_b32_e32 v28, v28, v17
	v_lshlrev_b32_e32 v28, 4, v28
	v_lshl_or_b32 v28, v16, 7, v28
	v_xor_b32_e32 v29, 64, v28
	v_lshrrev_b32_e32 v30, 2, v16
	v_xor_b32_e32 v30, v30, v17
	v_lshlrev_b32_e32 v30, 4, v30
	v_lshl_or_b32 v30, v16, 6, v30
	v_lshlrev_b32_e32 v31, 3, v10
	v_add_u32_e32 v31, 0x3800, v31
	v_lshlrev_b32_e32 v32, 3, v17
	v_add_u32_e32 v32, 0x4800, v32
	v_mov_b32_e32 v0, 0
	v_mov_b32_e32 v1, 0
	v_mov_b32_e32 v2, 0
	v_mov_b32_e32 v3, 0
	v_mov_b32_e32 v4, 0
	v_mov_b32_e32 v5, 0
	v_mov_b32_e32 v6, 0
	v_mov_b32_e32 v7, 0
	v_mov_b32_e32 v8, 0
	v_mov_b32_e32 v9, 0
	v_mov_b32_e32 v10, 0
	v_mov_b32_e32 v11, 0
	v_mov_b32_e32 v12, 0
	v_mov_b32_e32 v13, 0
	v_mov_b32_e32 v14, 0
	v_mov_b32_e32 v15, 0
	s_waitcnt vmcnt(0) lgkmcnt(0)
	s_mov_b32 s6, 0
	s_mov_b32 s7, 0
	s_mov_b32 s8, 0
	s_mov_b32 m0, s6
	s_nop 0
	global_load_lds_dwordx4 v18, s[10:11]
	global_load_lds_dwordx4 v18, s[10:11] offset:1024
	global_load_lds_dwordx4 v18, s[10:11] offset:2048
	global_load_lds_dwordx4 v18, s[10:11] offset:3072
	s_add_i32 m0, s6, 0x1000
	s_nop 0
	global_load_lds_dwordx4 v19, s[10:11]
	global_load_lds_dwordx4 v19, s[10:11] offset:1024
	global_load_lds_dwordx4 v19, s[10:11] offset:2048
	global_load_lds_dwordx4 v19, s[10:11] offset:3072
	s_add_i32 m0, s6, 0x2000
	s_nop 0
	global_load_lds_dwordx4 v20, s[10:11]
	global_load_lds_dwordx4 v20, s[10:11] offset:1024
	global_load_lds_dwordx4 v20, s[10:11] offset:2048
	global_load_lds_dwordx4 v20, s[10:11] offset:3072
	s_add_i32 m0, s6, 0x3000
	s_nop 0
	global_load_lds_dwordx4 v21, s[10:11]
	global_load_lds_dwordx4 v21, s[10:11] offset:1024
	global_load_lds_dwordx4 v22, s[10:11] offset:2048
	global_load_lds_dwordx4 v23, s[10:11] offset:3072
	s_add_i32 m0, s6, 0x4000
	s_nop 0
	global_load_lds_dwordx4 v24, s[10:11]
	global_load_lds_dwordx4 v24, s[10:11] offset:1024
	global_load_lds_dwordx4 v25, s[10:11] offset:2048
	s_add_u32 s10, s10, 0x7a00
	s_addc_u32 s11, s11, 0
	s_add_i32 s6, s6, 0x4c00
	s_mov_b32 m0, s6
	s_nop 0
	global_load_lds_dwordx4 v18, s[10:11]
	global_load_lds_dwordx4 v18, s[10:11] offset:1024
	global_load_lds_dwordx4 v18, s[10:11] offset:2048
	global_load_lds_dwordx4 v18, s[10:11] offset:3072
	s_add_i32 m0, s6, 0x1000
	s_nop 0
	global_load_lds_dwordx4 v19, s[10:11]
	global_load_lds_dwordx4 v19, s[10:11] offset:1024
	global_load_lds_dwordx4 v19, s[10:11] offset:2048
	global_load_lds_dwordx4 v19, s[10:11] offset:3072
	s_add_i32 m0, s6, 0x2000
	s_nop 0
	global_load_lds_dwordx4 v20, s[10:11]
	global_load_lds_dwordx4 v20, s[10:11] offset:1024
	global_load_lds_dwordx4 v20, s[10:11] offset:2048
	global_load_lds_dwordx4 v20, s[10:11] offset:3072
	s_add_i32 m0, s6, 0x3000
	s_nop 0
	global_load_lds_dwordx4 v21, s[10:11]
	global_load_lds_dwordx4 v21, s[10:11] offset:1024
	global_load_lds_dwordx4 v22, s[10:11] offset:2048
	global_load_lds_dwordx4 v23, s[10:11] offset:3072
	s_add_i32 m0, s6, 0x4000
	s_nop 0
	global_load_lds_dwordx4 v24, s[10:11]
	global_load_lds_dwordx4 v24, s[10:11] offset:1024
	global_load_lds_dwordx4 v25, s[10:11] offset:2048
	s_add_u32 s10, s10, 0x7a00
	s_addc_u32 s11, s11, 0
	s_add_i32 s6, s6, 0x4c00
.Ld2_loop:
	s_cmp_gt_u32 s8, 61
	s_cbranch_scc1 .Ld2_nodma
	s_mov_b32 m0, s6
	v_add_u32_e32 v33, s7, v28
	global_load_lds_dwordx4 v18, s[10:11]
	global_load_lds_dwordx4 v18, s[10:11] offset:1024
	global_load_lds_dwordx4 v18, s[10:11] offset:2048
	global_load_lds_dwordx4 v18, s[10:11] offset:3072
	s_add_i32 m0, s6, 0x1000
	v_add_u32_e32 v34, s7, v29
	global_load_lds_dwordx4 v19, s[10:11]
	global_load_lds_dwordx4 v19, s[10:11] offset:1024
	global_load_lds_dwordx4 v19, s[10:11] offset:2048
	global_load_lds_dwordx4 v19, s[10:11] offset:3072
	s_add_i32 m0, s6, 0x2000
	v_add_u32_e32 v35, s7, v30
	global_load_lds_dwordx4 v20, s[10:11]
	global_load_lds_dwordx4 v20, s[10:11] offset:1024
	global_load_lds_dwordx4 v20, s[10:11] offset:2048
	global_load_lds_dwordx4 v20, s[10:11] offset:3072
	s_add_i32 m0, s6, 0x3000
	v_add_u32_e32 v36, s7, v31
	global_load_lds_dwordx4 v21, s[10:11]
	global_load_lds_dwordx4 v21, s[10:11] offset:1024
	global_load_lds_dwordx4 v22, s[10:11] offset:2048
	global_load_lds_dwordx4 v23, s[10:11] offset:3072
	s_add_i32 m0, s6, 0x4000
	v_add_u32_e32 v37, s7, v32
	global_load_lds_dwordx4 v24, s[10:11]
	global_load_lds_dwordx4 v24, s[10:11] offset:1024
	global_load_lds_dwordx4 v25, s[10:11] offset:2048
	s_add_u32 s10, s10, 0x7a00
	s_addc_u32 s11, s11, 0
	s_add_i32 s6, s6, 0x4c00
	s_cmp_eq_u32 s6, 0x21400
	s_cselect_b32 s6, 0, s6
	s_cmp_lt_u32 s8, 2
	s_cbranch_scc1 .Ld2_headwait
	s_waitcnt vmcnt(54)
.Ld2_compute:
	ds_read_b128 v[40:43], v33
	ds_read_b128 v[48:51], v34
	ds_read2st64_b64 v[96:99], v36 offset1:1
	ds_read_b128 v[44:47], v33 offset:2048
	ds_read_b128 v[52:55], v34 offset:2048
	ds_read_b128 v[56:59], v33 offset:4096
	ds_read_b128 v[64:67], v34 offset:4096
	ds_read2st64_b64 v[100:103], v36 offset0:2 offset1:3
	ds_read_b128 v[60:63], v33 offset:6144
	ds_read_b128 v[68:71], v34 offset:6144
	ds_read_b128 v[72:75], v35 offset:8192
	ds_read_b128 v[76:79], v35 offset:9216
	ds_read2st64_b64 v[104:107], v36 offset0:4 offset1:5
	ds_read2st64_b64 v[112:115], v36 offset0:6 offset1:7
	ds_read2_b64 v[116:119], v37 offset1:4
	ds_read2_b64 v[120:123], v37 offset0:8 offset1:12
	ds_read_b128 v[80:83], v35 offset:10240
	ds_read_b128 v[84:87], v35 offset:11264
	ds_read_b128 v[88:91], v35 offset:12288
	ds_read_b128 v[92:95], v35 offset:13312
	v_cvt_pk_bf16_f32 v124, v0, v1
	v_cvt_pk_bf16_f32 v125, v2, v3
	v_cvt_pk_bf16_f32 v126, v4, v5
	v_cvt_pk_bf16_f32 v127, v6, v7
	v_cvt_pk_bf16_f32 v128, v8, v9
	v_cvt_pk_bf16_f32 v129, v10, v11
	v_cvt_pk_bf16_f32 v130, v12, v13
	v_cvt_pk_bf16_f32 v131, v14, v15
	s_waitcnt lgkmcnt(15)
	v_lshlrev_b32_e32 v132, 16, v96
	v_and_b32_e32 v133, 0xffff0000, v96
	v_lshlrev_b32_e32 v134, 16, v97
	v_and_b32_e32 v135, 0xffff0000, v97
	s_nop 1
	v_mfma_f32_16x16x32_bf16 v[132:135], v[40:43], v[124:127], v[132:135]
	v_lshlrev_b32_e32 v136, 16, v98
	v_and_b32_e32 v137, 0xffff0000, v98
	v_lshlrev_b32_e32 v138, 16, v99
	v_and_b32_e32 v139, 0xffff0000, v99
	v_mfma_f32_16x16x32_bf16 v[132:135], v[48:51], v[128:131], v[132:135]
	s_nop 0
	v_mfma_f32_16x16x32_bf16 v[136:139], v[44:47], v[124:127], v[136:139]
	s_waitcnt lgkmcnt(12)
	v_lshlrev_b32_e32 v140, 16, v100
	v_and_b32_e32 v141, 0xffff0000, v100
	v_lshlrev_b32_e32 v142, 16, v101
	v_and_b32_e32 v143, 0xffff0000, v101
	v_mfma_f32_16x16x32_bf16 v[136:139], v[52:55], v[128:131], v[136:139]
	v_lshlrev_b32_e32 v144, 16, v102
	v_and_b32_e32 v145, 0xffff0000, v102
	v_lshlrev_b32_e32 v146, 16, v103
	v_and_b32_e32 v147, 0xffff0000, v103
	v_mfma_f32_16x16x32_bf16 v[140:143], v[56:59], v[124:127], v[140:143]
	s_waitcnt lgkmcnt(10)
	v_mfma_f32_16x16x32_bf16 v[144:147], v[60:63], v[124:127], v[144:147]
	v_mfma_f32_16x16x32_bf16 v[140:143], v[64:67], v[128:131], v[140:143]
	v_mfma_f32_16x16x32_bf16 v[144:147], v[68:71], v[128:131], v[144:147]
	s_waitcnt lgkmcnt(4)
	v_lshlrev_b32_e32 v152, 16, v104
	v_and_b32_e32 v153, 0xffff0000, v104
	v_lshlrev_b32_e32 v154, 16, v105
	v_and_b32_e32 v155, 0xffff0000, v105
	v_lshlrev_b32_e32 v168, 16, v116
	v_and_b32_e32 v169, 0xffff0000, v116
	v_lshlrev_b32_e32 v170, 16, v117
	v_and_b32_e32 v171, 0xffff0000, v117
	v_pk_fma_f32 v[152:153], v[168:169], v[0:1], v[152:153]
	v_pk_fma_f32 v[154:155], v[170:171], v[2:3], v[154:155]
	v_lshlrev_b32_e32 v156, 16, v106
	v_and_b32_e32 v157, 0xffff0000, v106
	v_lshlrev_b32_e32 v158, 16, v107
	v_and_b32_e32 v159, 0xffff0000, v107
	v_lshlrev_b32_e32 v168, 16, v118
	v_and_b32_e32 v169, 0xffff0000, v118
	v_lshlrev_b32_e32 v170, 16, v119
	v_and_b32_e32 v171, 0xffff0000, v119
	v_pk_fma_f32 v[156:157], v[168:169], v[4:5], v[156:157]
	v_pk_fma_f32 v[158:159], v[170:171], v[6:7], v[158:159]
	v_lshlrev_b32_e32 v160, 16, v112
	v_and_b32_e32 v161, 0xffff0000, v112
	v_lshlrev_b32_e32 v162, 16, v113
	v_and_b32_e32 v163, 0xffff0000, v113
	v_lshlrev_b32_e32 v168, 16, v120
	v_and_b32_e32 v169, 0xffff0000, v120
	v_lshlrev_b32_e32 v170, 16, v121
	v_and_b32_e32 v171, 0xffff0000, v121
	v_pk_fma_f32 v[160:161], v[168:169], v[8:9], v[160:161]
	v_pk_fma_f32 v[162:163], v[170:171], v[10:11], v[162:163]
	v_lshlrev_b32_e32 v164, 16, v114
	v_and_b32_e32 v165, 0xffff0000, v114
	v_lshlrev_b32_e32 v166, 16, v115
	v_and_b32_e32 v167, 0xffff0000, v115
	v_lshlrev_b32_e32 v168, 16, v122
	v_and_b32_e32 v169, 0xffff0000, v122
	v_lshlrev_b32_e32 v170, 16, v123
	v_and_b32_e32 v171, 0xffff0000, v123
	v_pk_fma_f32 v[164:165], v[168:169], v[12:13], v[164:165]
	v_pk_fma_f32 v[166:167], v[170:171], v[14:15], v[166:167]
	v_cvt_pk_bf16_f32 v148, v132, v133
	v_cvt_pk_bf16_f32 v149, v134, v135
	v_cvt_pk_bf16_f32 v150, v136, v137
	v_cvt_pk_bf16_f32 v151, v138, v139
	s_nop 1
	v_mfma_f32_16x16x32_bf16 v[140:143], v[72:75], v[148:151], v[140:143]
	v_mfma_f32_16x16x32_bf16 v[144:147], v[76:79], v[148:151], v[144:147]
	s_waitcnt lgkmcnt(0)
	v_mfma_f32_16x16x32_bf16 v[0:3], v[80:83], v[148:151], v[152:155]
	v_mfma_f32_16x16x32_bf16 v[4:7], v[84:87], v[148:151], v[156:159]
	v_mfma_f32_16x16x32_bf16 v[8:11], v[88:91], v[148:151], v[160:163]
	v_mfma_f32_16x16x32_bf16 v[12:15], v[92:95], v[148:151], v[164:167]
	s_nop 1
	global_store_dword v26, v140, s[12:13]
	global_store_dword v26, v141, s[12:13] offset:1024
	global_store_dword v26, v142, s[12:13] offset:2048
	global_store_dword v26, v143, s[12:13] offset:3072
	global_store_dword v27, v144, s[12:13]
	global_store_dword v27, v145, s[12:13] offset:1024
	global_store_dword v27, v146, s[12:13] offset:2048
	global_store_dword v27, v147, s[12:13] offset:3072
	s_add_u32 s12, s12, 0x8000
	s_addc_u32 s13, s13, 0
	s_add_i32 s7, s7, 0x4c00
	s_cmp_eq_u32 s7, 0x21400
	s_cselect_b32 s7, 0, s7
	s_add_i32 s8, s8, 1
	s_cmp_lt_u32 s8, 64
	s_cbranch_scc1 .Ld2_loop
	s_branch .LBB0_598
.Ld2_nodma:
	v_add_u32_e32 v33, s7, v28
	v_add_u32_e32 v34, s7, v29
	v_add_u32_e32 v35, s7, v30
	v_add_u32_e32 v36, s7, v31
	v_add_u32_e32 v37, s7, v32
	s_waitcnt vmcnt(0)
	s_branch .Ld2_compute
.Ld2_headwait:
	s_cmp_eq_u32 s8, 0
	s_cbranch_scc1 .Ld2_wait0
	s_waitcnt vmcnt(46)
	s_branch .Ld2_compute

.LBB0_600:
	s_and_b64 vcc, exec, s[0:1]
	s_cbranch_vccz .LBB0_605
	v_readlane_b32 s100, v253, 11
	s_nop 0
	s_cmp_lt_u32 s100, 4
	s_cbranch_scc1 .LBB0_605
	s_mov_b32 s101, 0
.Lgmlp_again:
	s_mov_b32 s5, s89
	s_lshl_b32 s2, s5, 5
	s_and_b32 s3, s2, 32
	s_ashr_i32 s2, s5, 1
	s_lshl_b32 s10, s2, 7
	v_readlane_b32 s12, v252, 2
	s_ashr_i32 s11, s10, 31
	s_lshl_b32 s4, s56, 11
	v_readlane_b32 s20, v252, 10
	v_readlane_b32 s21, v252, 11
	s_add_u32 s4, s20, s4
	s_addc_u32 s8, s21, 0
	s_lshl_b64 s[6:7], s[10:11], 2
	s_add_u32 s6, s4, s6
	s_addc_u32 s7, s8, s7
	s_lshl_b32 s8, s2, 6
	v_readlane_b32 s13, v252, 3
	s_ashr_i32 s9, s8, 31
	s_mov_b64 s[0:1], s[78:79]
	s_lshl_b64 s[12:13], s[8:9], 1
	v_mbcnt_lo_u32_b32 v57, -1, 0
	v_mbcnt_hi_u32_b32 v57, -1, v57
	s_add_u32 s12, s0, s12
	v_bfe_u32 v47, v57, 4, 2
	v_and_b32_e32 v37, 15, v57
	s_addc_u32 s13, s1, s13
	v_lshlrev_b32_e32 v194, 3, v47
	v_lshl_add_u64 v[0:1], s[12:13], 0, v[194:195]
	s_mov_b64 s[12:13], 0x2040000
	v_or_b32_e32 v2, s3, v37
	v_readlane_b32 s4, v253, 36
	v_lshl_add_u64 v[0:1], v[0:1], 0, s[12:13]
	v_lshlrev_b32_e32 v4, 2, v2
	v_or_b32_e32 v2, s4, v2
	v_mad_i64_i32 v[2:3], s[12:13], v2, s86, v[0:1]
	s_or_b32 s2, s3, 16
	global_load_dwordx2 v[74:75], v[2:3], off
	global_load_dwordx2 v[72:73], v[2:3], off offset:32
	global_load_dwordx2 v[70:71], v[2:3], off offset:64
	global_load_dwordx2 v[68:69], v[2:3], off offset:96
	v_or_b32_e32 v2, s2, v37
	v_or_b32_e32 v2, s4, v2
	v_or_b32_e32 v5, 64, v37
	v_mad_i64_i32 v[2:3], s[12:13], v2, s86, v[0:1]
	v_or_b32_e32 v6, s3, v5
	global_load_dwordx2 v[64:65], v[2:3], off
	global_load_dwordx2 v[62:63], v[2:3], off offset:32
	global_load_dwordx2 v[60:61], v[2:3], off offset:64
	global_load_dwordx2 v[58:59], v[2:3], off offset:96
	v_or_b32_e32 v2, s4, v6
	v_mad_i64_i32 v[2:3], s[12:13], v2, s86, v[0:1]
	global_load_dword v66, v4, s[6:7]
	global_load_dword v56, v4, s[6:7] offset:64
	global_load_dword v46, v4, s[6:7] offset:256
	global_load_dwordx2 v[54:55], v[2:3], off
	global_load_dwordx2 v[52:53], v[2:3], off offset:32
	global_load_dwordx2 v[50:51], v[2:3], off offset:64
	global_load_dwordx2 v[48:49], v[2:3], off offset:96
	v_or_b32_e32 v2, s2, v5
	v_lshlrev_b32_e32 v3, 2, v6
	v_or_b32_e32 v2, s4, v2
	global_load_dword v36, v3, s[6:7] offset:64
	v_mad_i64_i32 v[0:1], s[6:7], v2, s86, v[0:1]
	global_load_dwordx2 v[44:45], v[0:1], off
	global_load_dwordx2 v[42:43], v[0:1], off offset:32
	global_load_dwordx2 v[40:41], v[0:1], off offset:64
	global_load_dwordx2 v[38:39], v[0:1], off offset:96
	s_cmpk_gt_i32 s5, 0x7f
	v_readlane_b32 s14, v252, 4
	v_readlane_b32 s15, v252, 5
	v_readlane_b32 s16, v252, 6
	v_readlane_b32 s17, v252, 7
	v_readlane_b32 s18, v252, 8
	v_readlane_b32 s19, v252, 9
	v_readlane_b32 s22, v252, 12
	v_readlane_b32 s23, v252, 13
	v_readlane_b32 s24, v252, 14
	v_readlane_b32 s25, v252, 15
	v_readlane_b32 s26, v252, 16
	v_readlane_b32 s27, v252, 17
	s_cbranch_scc1 .LBB0_604
	v_readlane_b32 s12, v252, 2
	v_readlane_b32 s13, v252, 3
	v_readlane_b32 s16, v252, 6
	v_readlane_b32 s12, v255, 41
	v_readlane_b32 s17, v252, 7
	v_readlane_b32 s13, v255, 42
	s_add_u32 s6, s16, s12
	v_readlane_b32 s14, v252, 4
	s_addc_u32 s7, s17, s13
	v_and_b32_e32 v4, 63, v57
	v_readlane_b32 s15, v252, 5
	s_add_u32 s12, s14, s12
	s_addc_u32 s13, s15, s13
	v_lshlrev_b32_e32 v194, 2, v4
	global_load_dword v67, v194, s[12:13]
	global_load_dword v106, v194, s[6:7]
	global_load_dword v107, v194, s[12:13] offset:256
	global_load_dword v108, v194, s[6:7] offset:256
	global_load_dword v110, v194, s[12:13] offset:512
	global_load_dword v111, v194, s[6:7] offset:512
	global_load_dword v112, v194, s[12:13] offset:768
	global_load_dword v113, v194, s[6:7] offset:768
	s_add_i32 s4, s5, 0xffffff80
	s_lshl_b32 s5, s5, 1
	s_add_i32 s5, s5, 0
	v_readlane_b32 s18, v252, 8
	v_readlane_b32 s20, v252, 10
	v_or_b32_e32 v6, 64, v4
	v_or_b32_e32 v8, 0x80, v4
	v_or_b32_e32 v10, 0xc0, v4
	v_mov_b32_e32 v5, s5
	s_movk_i32 s5, 0x108
	s_mov_b32 s20, 0x3b800000
	s_mov_b32 s18, 0x800000
	v_lshl_add_u64 v[0:1], s[12:13], 0, v[194:195]
	v_lshl_add_u64 v[2:3], s[6:7], 0, v[194:195]
	v_mad_u32_u24 v114, v4, s5, v5
	v_lshlrev_b32_e32 v194, 1, v4
	v_lshlrev_b32_e32 v4, 1, v6
	v_lshlrev_b32_e32 v6, 1, v8
	v_lshlrev_b32_e32 v8, 1, v10
	v_readlane_b32 s19, v252, 9
	v_readlane_b32 s21, v252, 11
	v_readlane_b32 s22, v252, 12
	v_readlane_b32 s23, v252, 13
	v_readlane_b32 s24, v252, 14
	v_readlane_b32 s25, v252, 15
	v_readlane_b32 s26, v252, 16
	v_readlane_b32 s27, v252, 17

.LBB0_604:
	v_readlane_b32 s4, v255, 29
	s_add_u32 s4, s0, s4
	v_or_b32_e32 v82, s10, v37
	s_addc_u32 s5, s1, 0
	v_lshlrev_b32_e32 v194, 4, v47
	v_or_b32_e32 v2, s3, v82
	v_lshl_add_u64 v[0:1], s[4:5], 0, v[194:195]
	s_mov_b64 s[4:5], 0x90a0000
	v_ashrrev_i32_e32 v3, 31, v2
	v_lshl_add_u64 v[76:77], v[0:1], 0, s[4:5]
	v_lshlrev_b64 v[2:3], 8, v[2:3]
	v_mov_b32_e32 v0, v192
	v_mov_b32_e32 v6, v192
	v_mov_b32_e32 v10, v192
	v_mov_b32_e32 v14, v192
	v_mov_b32_e32 v18, v192
	v_mov_b32_e32 v22, v192
	v_mov_b32_e32 v26, v192
	v_mov_b32_e32 v30, v192
	v_lshl_add_u64 v[2:3], v[76:77], 0, v[2:3]
	s_waitcnt vmcnt(0) lgkmcnt(0)
	s_barrier
	global_load_dwordx4 v[32:35], v[2:3], off
	v_or_b32_e32 v4, s2, v82
	v_ashrrev_i32_e32 v5, 31, v4
	v_lshlrev_b64 v[4:5], 8, v[4:5]
	v_lshl_add_u64 v[4:5], v[76:77], 0, v[4:5]
	global_load_dwordx4 v[78:81], v[4:5], off
	global_load_dwordx4 v[90:93], v[2:3], off offset:64
	v_or_b32_e32 v1, s8, v37
	s_movk_i32 s4, 0x108
	v_and_b32_e32 v2, 48, v57
	v_mul_lo_u32 v1, v1, s4
	v_add3_u32 v57, 0, v2, v1
	ds_read2_b64 v[86:89], v57 offset1:1
	v_mov_b32_e32 v1, v0
	v_add_u32_e32 v83, 0x1080, v57
	v_mov_b32_e32 v2, v0
	v_mov_b32_e32 v3, v0
	v_add_u32_e32 v84, 0x2100, v57
	v_add_u32_e32 v85, 0x3180, v57
	ds_read2_b64 v[94:97], v83 offset1:1
	ds_read2_b64 v[98:101], v84 offset1:1
	v_mov_b32_e32 v7, v6
	v_mov_b32_e32 v8, v6
	v_mov_b32_e32 v9, v6
	v_mov_b32_e32 v11, v10
	v_mov_b32_e32 v12, v10
	v_mov_b32_e32 v13, v10
	v_mov_b32_e32 v15, v14
	v_mov_b32_e32 v16, v14
	v_mov_b32_e32 v17, v14
	v_mov_b32_e32 v19, v18
	v_mov_b32_e32 v20, v18
	v_mov_b32_e32 v21, v18
	v_mov_b32_e32 v23, v22
	v_mov_b32_e32 v24, v22
	v_mov_b32_e32 v25, v22
	v_mov_b32_e32 v27, v26
	v_mov_b32_e32 v28, v26
	v_mov_b32_e32 v29, v26
	v_mov_b32_e32 v31, v30
	v_readlane_b32 s4, v253, 36
	s_waitcnt vmcnt(0) lgkmcnt(0)
	v_mfma_f32_16x16x32_bf16 v[110:113], v[86:89], v[78:81], v[18:21]
	v_or_b32_e32 v37, s4, v37
	s_mov_b64 s[4:5], 0x2040600
	v_mfma_f32_16x16x32_bf16 v[102:105], v[86:89], v[32:35], v[0:3]
	v_add_u32_e32 v86, 0x10c0, v57
	v_add_u32_e32 v87, 0x2140, v57
	v_add_u32_e32 v88, 0x31c0, v57
	ds_read2_b64 v[0:3], v85 offset1:1
	v_mfma_f32_16x16x32_bf16 v[6:9], v[94:97], v[32:35], v[6:9]
	ds_read2_b64 v[114:117], v87 offset1:1
	v_mfma_f32_16x16x32_bf16 v[10:13], v[98:101], v[32:35], v[10:13]
	s_waitcnt lgkmcnt(1)
	v_mfma_f32_16x16x32_bf16 v[14:17], v[0:3], v[32:35], v[14:17]
	v_mov_b32_e32 v32, v30
	v_mov_b32_e32 v33, v30
	v_mfma_f32_16x16x32_bf16 v[94:97], v[94:97], v[78:81], v[22:25]
	v_mfma_f32_16x16x32_bf16 v[98:101], v[98:101], v[78:81], v[26:29]
	v_mfma_f32_16x16x32_bf16 v[0:3], v[0:3], v[78:81], v[30:33]
	ds_read2_b64 v[78:81], v57 offset0:8 offset1:9
	s_waitcnt lgkmcnt(0)
	v_mfma_f32_16x16x32_bf16 v[28:31], v[78:81], v[90:93], v[102:105]
	s_nop 2
	ds_read2_b64 v[102:105], v86 offset1:1
	ds_read2_b64 v[32:35], v88 offset1:1
	s_waitcnt lgkmcnt(1)
	v_mfma_f32_16x16x32_bf16 v[24:27], v[102:105], v[90:93], v[6:9]
	v_mfma_f32_16x16x32_bf16 v[20:23], v[114:117], v[90:93], v[10:13]
	s_waitcnt lgkmcnt(0)
	v_mfma_f32_16x16x32_bf16 v[12:15], v[32:35], v[90:93], v[14:17]
	global_load_dwordx4 v[90:93], v[4:5], off offset:64
	v_lshlrev_b32_e32 v4, 2, v47
	s_waitcnt vmcnt(0) lgkmcnt(0)
	v_mfma_f32_16x16x32_bf16 v[8:11], v[102:105], v[90:93], v[94:97]
	s_nop 2
	v_lshlrev_b32_e32 v94, 16, v74
	v_mul_f32_e32 v47, 0x3d372713, v94
	v_mul_f32_e32 v47, v47, v94
	v_mov_b32_e32 v67, v94
	v_fmac_f32_e32 v67, v47, v67
	v_mul_f32_e32 v47, 0x3f4c422a, v67
	v_add_f32_e32 v47, v47, v47
	v_and_b32_e32 v95, 0xffff0000, v74
	v_mul_f32_e32 v47, 0xbfb8aa3b, v47
	v_mfma_f32_16x16x32_bf16 v[16:19], v[78:81], v[90:93], v[110:113]
	v_exp_f32_e32 v80, v47
	v_mul_f32_e32 v47, 0x3d372713, v95
	v_mul_f32_e32 v47, v47, v95
	v_mov_b32_e32 v67, v95
	v_fmac_f32_e32 v67, v47, v67
	v_mul_f32_e32 v47, 0x3f4c422a, v67
	v_add_f32_e32 v47, v47, v47
	v_mul_f32_e32 v47, 0xbfb8aa3b, v47
	v_exp_f32_e32 v81, v47
	v_mfma_f32_16x16x32_bf16 v[0:3], v[32:35], v[90:93], v[0:3]
	v_mov_b64_e32 v[32:33], s[0:1]
	v_or_b32_e32 v47, s3, v37
	v_pk_add_f32 v[34:35], v[80:81], 1.0 op_sel_hi:[1,0]
	v_mad_i64_i32 v[80:81], s[0:1], v47, s86, v[32:33]
	v_or_b32_e32 v78, s8, v4
	v_mfma_f32_16x16x32_bf16 v[4:7], v[114:117], v[90:93], v[98:101]
	v_lshl_add_u64 v[80:81], v[80:81], 0, s[4:5]
	v_rcp_f32_e32 v35, v35
	v_pk_add_f32 v[16:17], v[56:57], v[16:17] op_sel_hi:[0,1]
	v_lshlrev_b32_e32 v74, 16, v75
	v_mul_f32_e32 v67, 0x3d372713, v74
	v_mul_f32_e32 v67, v67, v74
	v_mov_b32_e32 v90, v74
	v_fmac_f32_e32 v90, v67, v90
	v_mul_f32_e32 v67, 0x3f4c422a, v90
	v_add_f32_e32 v67, v67, v67
	v_and_b32_e32 v75, 0xffff0000, v75
	v_mul_f32_e32 v67, 0xbfb8aa3b, v67
	v_exp_f32_e32 v90, v67
	v_mul_f32_e32 v67, 0x3d372713, v75
	v_mul_f32_e32 v67, v67, v75
	v_mov_b32_e32 v91, v75
	v_fmac_f32_e32 v91, v67, v91
	v_mul_f32_e32 v67, 0x3f4c422a, v91
	v_add_f32_e32 v67, v67, v67
	v_mul_f32_e32 v67, 0xbfb8aa3b, v67
	v_exp_f32_e32 v91, v67
	v_rcp_f32_e32 v34, v34
	s_nop 0
	v_pk_mul_f32 v[34:35], v[34:35], v[94:95]
	v_pk_add_f32 v[90:91], v[90:91], 1.0 op_sel_hi:[1,0]
	v_pk_add_f32 v[18:19], v[56:57], v[18:19] op_sel_hi:[0,1]
	v_pk_add_f32 v[8:9], v[56:57], v[8:9] op_sel_hi:[0,1]
	v_pk_add_f32 v[10:11], v[56:57], v[10:11] op_sel_hi:[0,1]
	v_pk_add_f32 v[4:5], v[56:57], v[4:5] op_sel_hi:[0,1]
	v_pk_add_f32 v[28:29], v[66:67], v[28:29] op_sel_hi:[0,1]
	v_pk_mul_f32 v[28:29], v[34:35], v[28:29]
	v_rcp_f32_e32 v35, v91
	v_pk_add_f32 v[6:7], v[56:57], v[6:7] op_sel_hi:[0,1]
	v_rcp_f32_e32 v34, v90
	s_nop 0
	v_pk_mul_f32 v[34:35], v[34:35], v[74:75]
	v_pk_add_f32 v[30:31], v[66:67], v[30:31] op_sel_hi:[0,1]
	v_pk_mul_f32 v[30:31], v[34:35], v[30:31]
	v_lshlrev_b32_e32 v34, 16, v72
	v_mul_f32_e32 v47, 0x3d372713, v34
	v_mul_f32_e32 v47, v47, v34
	v_mov_b32_e32 v67, v34
	v_fmac_f32_e32 v67, v47, v67
	v_mul_f32_e32 v47, 0x3f4c422a, v67
	v_add_f32_e32 v47, v47, v47
	v_and_b32_e32 v35, 0xffff0000, v72
	v_mul_f32_e32 v47, 0xbfb8aa3b, v47
	v_exp_f32_e32 v74, v47
	v_mul_f32_e32 v47, 0x3d372713, v35
	v_mul_f32_e32 v47, v47, v35
	v_mov_b32_e32 v67, v35
	v_fmac_f32_e32 v67, v47, v67
	v_mul_f32_e32 v47, 0x3f4c422a, v67
	v_add_f32_e32 v47, v47, v47
	v_mul_f32_e32 v47, 0xbfb8aa3b, v47
	v_exp_f32_e32 v75, v47
	v_cvt_pk_bf16_f32 v91, v30, v31
	v_ashrrev_i32_e32 v79, 31, v78
	v_cvt_pk_bf16_f32 v90, v28, v29
	v_pk_add_f32 v[30:31], v[74:75], 1.0 op_sel_hi:[1,0]
	v_lshlrev_b64 v[28:29], 1, v[78:79]
	v_lshl_add_u64 v[74:75], v[80:81], 0, v[28:29]
	global_store_dwordx2 v[74:75], v[90:91], off
	v_pk_add_f32 v[0:1], v[56:57], v[0:1] op_sel_hi:[0,1]
	v_rcp_f32_e32 v31, v31
	v_pk_add_f32 v[2:3], v[56:57], v[2:3] op_sel_hi:[0,1]
	v_lshlrev_b32_e32 v72, 16, v73
	v_mul_f32_e32 v74, 0x3d372713, v72
	v_mul_f32_e32 v74, v74, v72
	v_mov_b32_e32 v75, v72
	v_and_b32_e32 v73, 0xffff0000, v73
	v_fmac_f32_e32 v75, v74, v75
	v_mul_f32_e32 v74, 0x3f4c422a, v75
	v_mul_f32_e32 v75, 0x3d372713, v73
	v_mul_f32_e32 v75, v75, v73
	v_mov_b32_e32 v89, v73
	v_fmac_f32_e32 v89, v75, v89
	v_mul_f32_e32 v75, 0x3f4c422a, v89
	v_add_f32_e32 v74, v74, v74
	v_add_f32_e32 v75, v75, v75
	v_mul_f32_e32 v74, 0xbfb8aa3b, v74
	v_mul_f32_e32 v75, 0xbfb8aa3b, v75
	v_exp_f32_e32 v74, v74
	v_exp_f32_e32 v75, v75
	v_rcp_f32_e32 v30, v30
	s_nop 0
	v_pk_mul_f32 v[30:31], v[30:31], v[34:35]
	v_pk_add_f32 v[74:75], v[74:75], 1.0 op_sel_hi:[1,0]
	s_nop 0
	v_pk_add_f32 v[24:25], v[66:67], v[24:25] op_sel_hi:[0,1]
	v_pk_mul_f32 v[24:25], v[30:31], v[24:25]
	v_rcp_f32_e32 v31, v75
	v_rcp_f32_e32 v30, v74
	s_nop 0
	v_pk_mul_f32 v[30:31], v[30:31], v[72:73]
	v_pk_add_f32 v[26:27], v[66:67], v[26:27] op_sel_hi:[0,1]
	v_lshlrev_b32_e32 v34, 16, v70
	v_pk_mul_f32 v[26:27], v[30:31], v[26:27]
	v_mul_f32_e32 v31, 0x3d372713, v34
	v_mul_f32_e32 v31, v31, v34
	v_mov_b32_e32 v47, v34
	v_fmac_f32_e32 v47, v31, v47
	v_mul_f32_e32 v31, 0x3f4c422a, v47
	v_add_f32_e32 v31, v31, v31
	v_and_b32_e32 v35, 0xffff0000, v70
	v_mul_f32_e32 v31, 0xbfb8aa3b, v31
	v_exp_f32_e32 v72, v31
	v_mul_f32_e32 v31, 0x3d372713, v35
	v_mul_f32_e32 v31, v31, v35
	v_mov_b32_e32 v47, v35
	v_fmac_f32_e32 v47, v31, v47
	v_mul_f32_e32 v31, 0x3f4c422a, v47
	v_add_f32_e32 v31, v31, v31
	v_mul_f32_e32 v31, 0xbfb8aa3b, v31
	v_exp_f32_e32 v73, v31
	v_cvt_pk_bf16_f32 v24, v24, v25
	v_cvt_pk_bf16_f32 v25, v26, v27
	v_or_b32_e32 v30, 16, v78
	v_pk_add_f32 v[26:27], v[72:73], 1.0 op_sel_hi:[1,0]
	v_ashrrev_i32_e32 v31, 31, v30
	v_lshlrev_b64 v[30:31], 1, v[30:31]
	v_lshl_add_u64 v[72:73], v[80:81], 0, v[30:31]
	global_store_dwordx2 v[72:73], v[24:25], off
	v_rcp_f32_e32 v25, v27
	v_lshlrev_b32_e32 v70, 16, v71
	v_mul_f32_e32 v47, 0x3d372713, v70
	v_mul_f32_e32 v47, v47, v70
	v_mov_b32_e32 v67, v70
	v_fmac_f32_e32 v67, v47, v67
	v_mul_f32_e32 v47, 0x3f4c422a, v67
	v_add_f32_e32 v47, v47, v47
	v_and_b32_e32 v71, 0xffff0000, v71
	v_mul_f32_e32 v47, 0xbfb8aa3b, v47
	v_exp_f32_e32 v72, v47
	v_mul_f32_e32 v47, 0x3d372713, v71
	v_mul_f32_e32 v47, v47, v71
	v_mov_b32_e32 v67, v71
	v_fmac_f32_e32 v67, v47, v67
	v_mul_f32_e32 v47, 0x3f4c422a, v67
	v_add_f32_e32 v47, v47, v47
	v_mul_f32_e32 v47, 0xbfb8aa3b, v47
	v_exp_f32_e32 v73, v47
	v_rcp_f32_e32 v24, v26
	s_nop 0
	v_pk_mul_f32 v[24:25], v[24:25], v[34:35]
	v_pk_add_f32 v[26:27], v[72:73], 1.0 op_sel_hi:[1,0]
	s_nop 0
	v_pk_add_f32 v[20:21], v[66:67], v[20:21] op_sel_hi:[0,1]
	v_pk_mul_f32 v[20:21], v[24:25], v[20:21]
	v_rcp_f32_e32 v25, v27
	v_rcp_f32_e32 v24, v26
	s_nop 0
	v_pk_mul_f32 v[24:25], v[24:25], v[70:71]
	v_pk_add_f32 v[22:23], v[66:67], v[22:23] op_sel_hi:[0,1]
	v_lshlrev_b32_e32 v26, 16, v68
	v_pk_mul_f32 v[22:23], v[24:25], v[22:23]
	v_mul_f32_e32 v25, 0x3d372713, v26
	v_mul_f32_e32 v25, v25, v26
	v_mov_b32_e32 v34, v26
	v_fmac_f32_e32 v34, v25, v34
	v_mul_f32_e32 v25, 0x3f4c422a, v34
	v_add_f32_e32 v25, v25, v25
	v_and_b32_e32 v27, 0xffff0000, v68
	v_mul_f32_e32 v25, 0xbfb8aa3b, v25
	v_exp_f32_e32 v34, v25
	v_mul_f32_e32 v25, 0x3d372713, v27
	v_mul_f32_e32 v25, v25, v27
	v_mov_b32_e32 v35, v27
	v_fmac_f32_e32 v35, v25, v35
	v_mul_f32_e32 v25, 0x3f4c422a, v35
	v_add_f32_e32 v25, v25, v25
	v_mul_f32_e32 v25, 0xbfb8aa3b, v25
	v_exp_f32_e32 v35, v25
	v_cvt_pk_bf16_f32 v20, v20, v21
	v_cvt_pk_bf16_f32 v21, v22, v23
	v_or_b32_e32 v24, 32, v78
	v_pk_add_f32 v[22:23], v[34:35], 1.0 op_sel_hi:[1,0]
	v_ashrrev_i32_e32 v25, 31, v24
	v_lshlrev_b64 v[34:35], 1, v[24:25]
	v_lshl_add_u64 v[24:25], v[80:81], 0, v[34:35]
	global_store_dwordx2 v[24:25], v[20:21], off
	v_rcp_f32_e32 v21, v23
	v_lshlrev_b32_e32 v24, 16, v69
	v_mul_f32_e32 v67, 0x3d372713, v24
	v_mul_f32_e32 v67, v67, v24
	v_mov_b32_e32 v68, v24
	v_fmac_f32_e32 v68, v67, v68
	v_mul_f32_e32 v67, 0x3f4c422a, v68
	v_add_f32_e32 v67, v67, v67
	v_and_b32_e32 v25, 0xffff0000, v69
	v_mul_f32_e32 v67, 0xbfb8aa3b, v67
	v_exp_f32_e32 v68, v67
	v_mul_f32_e32 v67, 0x3d372713, v25
	v_mul_f32_e32 v67, v67, v25
	v_mov_b32_e32 v69, v25
	v_fmac_f32_e32 v69, v67, v69
	v_mul_f32_e32 v67, 0x3f4c422a, v69
	v_add_f32_e32 v67, v67, v67
	v_mul_f32_e32 v67, 0xbfb8aa3b, v67
	v_exp_f32_e32 v69, v67
	v_rcp_f32_e32 v20, v22
	s_nop 0
	v_pk_mul_f32 v[20:21], v[20:21], v[26:27]
	v_pk_add_f32 v[22:23], v[68:69], 1.0 op_sel_hi:[1,0]
	s_nop 0
	v_pk_add_f32 v[12:13], v[66:67], v[12:13] op_sel_hi:[0,1]
	v_pk_mul_f32 v[12:13], v[20:21], v[12:13]
	v_rcp_f32_e32 v21, v23
	v_rcp_f32_e32 v20, v22
	s_nop 0
	v_pk_mul_f32 v[20:21], v[20:21], v[24:25]
	v_pk_add_f32 v[14:15], v[66:67], v[14:15] op_sel_hi:[0,1]
	v_pk_mul_f32 v[14:15], v[20:21], v[14:15]
	v_or_b32_e32 v20, 48, v78
	v_cvt_pk_bf16_f32 v12, v12, v13
	v_cvt_pk_bf16_f32 v13, v14, v15
	v_ashrrev_i32_e32 v21, 31, v20
	v_lshlrev_b32_e32 v14, 16, v64
	v_lshlrev_b64 v[66:67], 1, v[20:21]
	v_mul_f32_e32 v20, 0x3d372713, v14
	v_mul_f32_e32 v20, v20, v14
	v_mov_b32_e32 v21, v14
	v_and_b32_e32 v15, 0xffff0000, v64
	v_fmac_f32_e32 v21, v20, v21
	v_mul_f32_e32 v20, 0x3f4c422a, v21
	v_mul_f32_e32 v21, 0x3d372713, v15
	v_mul_f32_e32 v21, v21, v15
	v_mov_b32_e32 v22, v15
	v_fmac_f32_e32 v22, v21, v22
	v_mul_f32_e32 v21, 0x3f4c422a, v22
	v_add_f32_e32 v20, v20, v20
	v_add_f32_e32 v21, v21, v21
	v_mul_f32_e32 v20, 0xbfb8aa3b, v20
	v_mul_f32_e32 v21, 0xbfb8aa3b, v21
	v_exp_f32_e32 v20, v20
	v_exp_f32_e32 v21, v21
	v_lshl_add_u64 v[22:23], v[80:81], 0, v[66:67]
	global_store_dwordx2 v[22:23], v[12:13], off
	v_or_b32_e32 v12, s2, v37
	v_pk_add_f32 v[20:21], v[20:21], 1.0 op_sel_hi:[1,0]
	v_mad_i64_i32 v[12:13], s[0:1], v12, s86, v[32:33]
	v_lshl_add_u64 v[12:13], v[12:13], 0, s[4:5]
	v_or_b32_e32 v37, 64, v37
	v_rcp_f32_e32 v21, v21
	v_lshlrev_b32_e32 v22, 16, v65
	v_mul_f32_e32 v24, 0x3d372713, v22
	v_mul_f32_e32 v24, v24, v22
	v_mov_b32_e32 v25, v22
	v_and_b32_e32 v23, 0xffff0000, v65
	v_fmac_f32_e32 v25, v24, v25
	v_mul_f32_e32 v24, 0x3f4c422a, v25
	v_mul_f32_e32 v25, 0x3d372713, v23
	v_mul_f32_e32 v25, v25, v23
	v_mov_b32_e32 v64, v23
	v_fmac_f32_e32 v64, v25, v64
	v_mul_f32_e32 v25, 0x3f4c422a, v64
	v_add_f32_e32 v24, v24, v24
	v_add_f32_e32 v25, v25, v25
	v_mul_f32_e32 v24, 0xbfb8aa3b, v24
	v_mul_f32_e32 v25, 0xbfb8aa3b, v25
	v_exp_f32_e32 v24, v24
	v_exp_f32_e32 v25, v25
	v_rcp_f32_e32 v20, v20
	s_nop 0
	v_pk_mul_f32 v[14:15], v[20:21], v[14:15]
	v_pk_add_f32 v[24:25], v[24:25], 1.0 op_sel_hi:[1,0]
	v_pk_mul_f32 v[14:15], v[14:15], v[16:17]
	s_nop 0
	v_cvt_pk_bf16_f32 v14, v14, v15
	v_add_u32_e32 v47, 0x1100, v57
	v_rcp_f32_e32 v17, v25
	v_rcp_f32_e32 v16, v24
	v_lshlrev_b32_e32 v20, 16, v62
	v_pk_mul_f32 v[16:17], v[16:17], v[22:23]
	v_mul_f32_e32 v22, 0x3d372713, v20
	v_mul_f32_e32 v22, v22, v20
	v_mov_b32_e32 v23, v20
	v_and_b32_e32 v21, 0xffff0000, v62
	v_fmac_f32_e32 v23, v22, v23
	v_mul_f32_e32 v22, 0x3f4c422a, v23
	v_mul_f32_e32 v23, 0x3d372713, v21
	v_mul_f32_e32 v23, v23, v21
	v_mov_b32_e32 v24, v21
	v_fmac_f32_e32 v24, v23, v24
	v_mul_f32_e32 v23, 0x3f4c422a, v24
	v_add_f32_e32 v22, v22, v22
	v_add_f32_e32 v23, v23, v23
	v_mul_f32_e32 v22, 0xbfb8aa3b, v22
	v_mul_f32_e32 v23, 0xbfb8aa3b, v23
	v_exp_f32_e32 v22, v22
	v_exp_f32_e32 v23, v23
	v_pk_mul_f32 v[16:17], v[16:17], v[18:19]
	v_mov_b32_e32 v62, v195
	v_cvt_pk_bf16_f32 v15, v16, v17
	v_pk_add_f32 v[18:19], v[22:23], 1.0 op_sel_hi:[1,0]
	v_lshl_add_u64 v[16:17], v[12:13], 0, v[28:29]
	global_store_dwordx2 v[16:17], v[14:15], off
	v_rcp_f32_e32 v15, v19
	v_lshlrev_b32_e32 v16, 16, v63
	v_mul_f32_e32 v22, 0x3d372713, v16
	v_mul_f32_e32 v22, v22, v16
	v_mov_b32_e32 v23, v16
	v_and_b32_e32 v17, 0xffff0000, v63
	v_fmac_f32_e32 v23, v22, v23
	v_mul_f32_e32 v22, 0x3f4c422a, v23
	v_mul_f32_e32 v23, 0x3d372713, v17
	v_mul_f32_e32 v23, v23, v17
	v_mov_b32_e32 v25, v17
	v_fmac_f32_e32 v25, v23, v25
	v_mul_f32_e32 v23, 0x3f4c422a, v25
	v_add_f32_e32 v22, v22, v22
	v_add_f32_e32 v23, v23, v23
	v_mul_f32_e32 v22, 0xbfb8aa3b, v22
	v_mul_f32_e32 v23, 0xbfb8aa3b, v23
	v_exp_f32_e32 v22, v22
	v_exp_f32_e32 v23, v23
	v_rcp_f32_e32 v14, v18
	s_nop 0
	v_pk_mul_f32 v[14:15], v[14:15], v[20:21]
	v_pk_add_f32 v[18:19], v[22:23], 1.0 op_sel_hi:[1,0]
	v_pk_mul_f32 v[8:9], v[14:15], v[8:9]
	s_nop 0
	v_cvt_pk_bf16_f32 v8, v8, v9
	v_mov_b32_e32 v24, v192
	v_rcp_f32_e32 v15, v19
	v_rcp_f32_e32 v14, v18
	s_nop 0
	v_pk_mul_f32 v[14:15], v[14:15], v[16:17]
	v_lshlrev_b32_e32 v16, 16, v60
	v_mul_f32_e32 v18, 0x3d372713, v16
	v_mul_f32_e32 v18, v18, v16
	v_mov_b32_e32 v19, v16
	v_and_b32_e32 v17, 0xffff0000, v60
	v_fmac_f32_e32 v19, v18, v19
	v_mul_f32_e32 v18, 0x3f4c422a, v19
	v_mul_f32_e32 v19, 0x3d372713, v17
	v_mul_f32_e32 v19, v19, v17
	v_mov_b32_e32 v20, v17
	v_fmac_f32_e32 v20, v19, v20
	v_mul_f32_e32 v19, 0x3f4c422a, v20
	v_add_f32_e32 v18, v18, v18
	v_add_f32_e32 v19, v19, v19
	v_mul_f32_e32 v18, 0xbfb8aa3b, v18
	v_mul_f32_e32 v19, 0xbfb8aa3b, v19
	v_exp_f32_e32 v18, v18
	v_exp_f32_e32 v19, v19
	v_pk_mul_f32 v[10:11], v[14:15], v[10:11]
	v_pk_add_f32 v[14:15], v[18:19], 1.0 op_sel_hi:[1,0]
	s_nop 0
	v_cvt_pk_bf16_f32 v9, v10, v11
	v_lshl_add_u64 v[10:11], v[12:13], 0, v[30:31]
	global_store_dwordx2 v[10:11], v[8:9], off
	v_rcp_f32_e32 v9, v15
	v_lshlrev_b32_e32 v10, 16, v61
	v_mul_f32_e32 v18, 0x3d372713, v10
	v_mul_f32_e32 v18, v18, v10
	v_mov_b32_e32 v19, v10
	v_and_b32_e32 v11, 0xffff0000, v61
	v_fmac_f32_e32 v19, v18, v19
	v_mul_f32_e32 v18, 0x3f4c422a, v19
	v_mul_f32_e32 v19, 0x3d372713, v11
	v_mul_f32_e32 v19, v19, v11
	v_mov_b32_e32 v21, v11
	v_fmac_f32_e32 v21, v19, v21
	v_mul_f32_e32 v19, 0x3f4c422a, v21
	v_add_f32_e32 v18, v18, v18
	v_add_f32_e32 v19, v19, v19
	v_mul_f32_e32 v18, 0xbfb8aa3b, v18
	v_mul_f32_e32 v19, 0xbfb8aa3b, v19
	v_exp_f32_e32 v18, v18
	v_exp_f32_e32 v19, v19
	v_rcp_f32_e32 v8, v14
	s_nop 0
	v_pk_mul_f32 v[8:9], v[8:9], v[16:17]
	v_pk_add_f32 v[14:15], v[18:19], 1.0 op_sel_hi:[1,0]
	v_pk_mul_f32 v[4:5], v[8:9], v[4:5]
	s_nop 0
	v_cvt_pk_bf16_f32 v4, v4, v5
	v_mov_b32_e32 v20, v192
	v_rcp_f32_e32 v9, v15
	v_rcp_f32_e32 v8, v14
	s_nop 0
	v_pk_mul_f32 v[8:9], v[8:9], v[10:11]
	v_lshlrev_b32_e32 v10, 16, v58
	v_mul_f32_e32 v14, 0x3d372713, v10
	v_mul_f32_e32 v14, v14, v10
	v_mov_b32_e32 v15, v10
	v_and_b32_e32 v11, 0xffff0000, v58
	v_fmac_f32_e32 v15, v14, v15
	v_mul_f32_e32 v14, 0x3f4c422a, v15
	v_mul_f32_e32 v15, 0x3d372713, v11
	v_mul_f32_e32 v15, v15, v11
	v_mov_b32_e32 v16, v11
	v_fmac_f32_e32 v16, v15, v16
	v_mul_f32_e32 v15, 0x3f4c422a, v16
	v_add_f32_e32 v14, v14, v14
	v_add_f32_e32 v15, v15, v15
	v_mul_f32_e32 v14, 0xbfb8aa3b, v14
	v_mul_f32_e32 v15, 0xbfb8aa3b, v15
	v_exp_f32_e32 v14, v14
	v_exp_f32_e32 v15, v15
	v_pk_mul_f32 v[6:7], v[8:9], v[6:7]
	v_mov_b32_e32 v58, v192
	v_cvt_pk_bf16_f32 v5, v6, v7
	v_pk_add_f32 v[8:9], v[14:15], 1.0 op_sel_hi:[1,0]
	v_lshl_add_u64 v[6:7], v[12:13], 0, v[34:35]
	global_store_dwordx2 v[6:7], v[4:5], off
	v_rcp_f32_e32 v5, v9
	v_lshlrev_b32_e32 v6, 16, v59
	v_mul_f32_e32 v14, 0x3d372713, v6
	v_mul_f32_e32 v14, v14, v6
	v_mov_b32_e32 v15, v6
	v_and_b32_e32 v7, 0xffff0000, v59
	v_fmac_f32_e32 v15, v14, v15
	v_mul_f32_e32 v14, 0x3f4c422a, v15
	v_mul_f32_e32 v15, 0x3d372713, v7
	v_mul_f32_e32 v15, v15, v7
	v_mov_b32_e32 v17, v7
	v_fmac_f32_e32 v17, v15, v17
	v_mul_f32_e32 v15, 0x3f4c422a, v17
	v_add_f32_e32 v14, v14, v14
	v_add_f32_e32 v15, v15, v15
	v_mul_f32_e32 v14, 0xbfb8aa3b, v14
	v_mul_f32_e32 v15, 0xbfb8aa3b, v15
	v_exp_f32_e32 v14, v14
	v_exp_f32_e32 v15, v15
	v_rcp_f32_e32 v4, v8
	s_nop 0
	v_pk_mul_f32 v[4:5], v[4:5], v[10:11]
	v_pk_add_f32 v[8:9], v[14:15], 1.0 op_sel_hi:[1,0]
	v_pk_mul_f32 v[0:1], v[4:5], v[0:1]
	s_nop 0
	v_cvt_pk_bf16_f32 v0, v0, v1
	v_mov_b32_e32 v16, v192
	v_rcp_f32_e32 v5, v9
	v_rcp_f32_e32 v4, v8
	s_nop 0
	v_pk_mul_f32 v[4:5], v[4:5], v[6:7]
	v_mov_b32_e32 v8, v192
	v_pk_mul_f32 v[2:3], v[4:5], v[2:3]
	v_or_b32_e32 v5, 64, v82
	v_cvt_pk_bf16_f32 v1, v2, v3
	v_lshl_add_u64 v[2:3], v[12:13], 0, v[66:67]
	global_store_dwordx2 v[2:3], v[0:1], off
	v_or_b32_e32 v0, s3, v5
	v_ashrrev_i32_e32 v1, 31, v0
	v_lshlrev_b64 v[0:1], 8, v[0:1]
	v_lshl_add_u64 v[2:3], v[76:77], 0, v[0:1]
	v_or_b32_e32 v0, s2, v5
	v_ashrrev_i32_e32 v1, 31, v0
	v_mov_b32_e32 v4, v192
	v_mov_b32_e32 v12, v192
	v_lshlrev_b64 v[0:1], 8, v[0:1]
	global_load_dwordx4 v[68:71], v[2:3], off
	v_lshl_add_u64 v[0:1], v[76:77], 0, v[0:1]
	global_load_dwordx4 v[72:75], v[0:1], off
	global_load_dwordx4 v[76:79], v[2:3], off offset:64
	ds_read2_b64 v[90:93], v57 offset1:1
	ds_read2_b64 v[80:83], v83 offset1:1
	ds_read2_b64 v[94:97], v84 offset1:1
	ds_read2_b64 v[98:101], v85 offset1:1
	v_mov_b32_e32 v9, v8
	v_mov_b32_e32 v5, v4
	v_mov_b32_e32 v6, v4
	v_mov_b32_e32 v7, v4
	v_mov_b32_e32 v10, v8
	v_mov_b32_e32 v11, v8
	v_mov_b32_e32 v13, v12
	v_mov_b32_e32 v14, v12
	v_mov_b32_e32 v15, v12
	v_mov_b32_e32 v17, v16
	v_mov_b32_e32 v18, v16
	v_mov_b32_e32 v19, v16
	v_mov_b32_e32 v21, v20
	v_mov_b32_e32 v22, v20
	v_mov_b32_e32 v23, v20
	v_mov_b32_e32 v25, v24
	v_mov_b32_e32 v26, v24
	v_mov_b32_e32 v27, v24
	v_mov_b32_e32 v59, v58
	v_mov_b32_e32 v60, v58
	v_mov_b32_e32 v61, v58
	v_mov_b32_e32 v63, v62
	v_mov_b32_e32 v64, v62
	v_mov_b32_e32 v65, v62
	s_waitcnt vmcnt(0) lgkmcnt(0)
	v_mfma_f32_16x16x32_bf16 v[4:7], v[90:93], v[68:71], v[4:7]
	v_mfma_f32_16x16x32_bf16 v[8:11], v[80:83], v[68:71], v[8:11]
	v_mfma_f32_16x16x32_bf16 v[12:15], v[94:97], v[68:71], v[12:15]
	v_mfma_f32_16x16x32_bf16 v[16:19], v[98:101], v[68:71], v[16:19]
	ds_read2_b64 v[68:71], v57 offset0:8 offset1:9
	v_mfma_f32_16x16x32_bf16 v[20:23], v[90:93], v[72:75], v[20:23]
	v_mfma_f32_16x16x32_bf16 v[24:27], v[80:83], v[72:75], v[24:27]
	ds_read2_b64 v[80:83], v87 offset1:1
	v_mfma_f32_16x16x32_bf16 v[58:61], v[94:97], v[72:75], v[58:61]
	v_mfma_f32_16x16x32_bf16 v[62:65], v[98:101], v[72:75], v[62:65]
	ds_read2_b64 v[72:75], v86 offset1:1
	ds_read2_b64 v[84:87], v88 offset1:1
	s_waitcnt lgkmcnt(3)
	v_mfma_f32_16x16x32_bf16 v[4:7], v[68:71], v[76:79], v[4:7]
	s_waitcnt lgkmcnt(1)
	v_mfma_f32_16x16x32_bf16 v[8:11], v[72:75], v[76:79], v[8:11]
	v_mfma_f32_16x16x32_bf16 v[12:15], v[80:83], v[76:79], v[12:15]
	s_waitcnt lgkmcnt(0)
	v_mfma_f32_16x16x32_bf16 v[16:19], v[84:87], v[76:79], v[16:19]
	global_load_dwordx4 v[76:79], v[0:1], off offset:64
	s_waitcnt vmcnt(0) lgkmcnt(0)
	v_mfma_f32_16x16x32_bf16 v[20:23], v[68:71], v[76:79], v[20:23]
	global_load_dwordx4 v[68:71], v[2:3], off offset:128
	v_mfma_f32_16x16x32_bf16 v[24:27], v[72:75], v[76:79], v[24:27]
	ds_read2_b64 v[72:75], v57 offset0:16 offset1:17
	v_mfma_f32_16x16x32_bf16 v[58:61], v[80:83], v[76:79], v[58:61]
	v_mfma_f32_16x16x32_bf16 v[62:65], v[84:87], v[76:79], v[62:65]
	ds_read2_b64 v[76:79], v47 offset1:1
	v_add_u32_e32 v47, 0x2180, v57
	ds_read2_b64 v[80:83], v47 offset1:1
	v_add_u32_e32 v47, 0x3200, v57
	ds_read2_b64 v[84:87], v47 offset1:1
	s_waitcnt vmcnt(0) lgkmcnt(0)
	v_mfma_f32_16x16x32_bf16 v[4:7], v[72:75], v[68:71], v[4:7]
	v_or_b32_e32 v47, s3, v37
	v_mfma_f32_16x16x32_bf16 v[8:11], v[76:79], v[68:71], v[8:11]
	v_mfma_f32_16x16x32_bf16 v[12:15], v[80:83], v[68:71], v[12:15]
	v_mfma_f32_16x16x32_bf16 v[16:19], v[84:87], v[68:71], v[16:19]
	global_load_dwordx4 v[68:71], v[0:1], off offset:128
	s_waitcnt vmcnt(0) lgkmcnt(0)
	v_mfma_f32_16x16x32_bf16 v[58:61], v[80:83], v[68:71], v[58:61]
	global_load_dwordx4 v[80:83], v[2:3], off offset:192
	v_add_u32_e32 v2, 0x1140, v57
	v_mfma_f32_16x16x32_bf16 v[72:75], v[72:75], v[68:71], v[20:23]
	v_mfma_f32_16x16x32_bf16 v[76:79], v[76:79], v[68:71], v[24:27]
	v_mfma_f32_16x16x32_bf16 v[62:65], v[84:87], v[68:71], v[62:65]
	ds_read2_b64 v[68:71], v57 offset0:24 offset1:25
	s_waitcnt vmcnt(0) lgkmcnt(0)
	v_mfma_f32_16x16x32_bf16 v[84:87], v[68:71], v[80:83], v[4:7]
	s_nop 2
	v_add_u32_e32 v6, 0x21c0, v57
	ds_read2_b64 v[2:5], v2 offset1:1
	ds_read2_b64 v[88:91], v6 offset1:1
	v_add_u32_e32 v6, 0x3240, v57
	ds_read2_b64 v[92:95], v6 offset1:1
	s_waitcnt lgkmcnt(2)
	v_mfma_f32_16x16x32_bf16 v[24:27], v[2:5], v[80:83], v[8:11]
	s_waitcnt lgkmcnt(1)
	v_mfma_f32_16x16x32_bf16 v[20:23], v[88:91], v[80:83], v[12:15]
	s_waitcnt lgkmcnt(0)
	v_mfma_f32_16x16x32_bf16 v[16:19], v[92:95], v[80:83], v[16:19]
	global_load_dwordx4 v[80:83], v[0:1], off offset:192
	s_waitcnt vmcnt(0) lgkmcnt(0)
	v_mfma_f32_16x16x32_bf16 v[8:11], v[2:5], v[80:83], v[76:79]
	s_nop 7
	v_pk_add_f32 v[8:9], v[36:37], v[8:9] op_sel_hi:[0,1]
	v_mfma_f32_16x16x32_bf16 v[4:7], v[88:91], v[80:83], v[58:61]
	v_add_f32_e64 v10, v36, v10
	v_add_f32_e64 v11, v36, v11
	s_nop 0
	v_lshlrev_b32_e32 v58, 16, v54
	v_mul_f32_e32 v0, 0x3d372713, v58
	v_mul_f32_e32 v0, v0, v58
	v_mov_b32_e32 v1, v58
	v_fmac_f32_e32 v1, v0, v1
	v_mul_f32_e32 v0, 0x3f4c422a, v1
	v_add_f32_e32 v0, v0, v0
	v_and_b32_e32 v59, 0xffff0000, v54
	v_mul_f32_e32 v0, 0xbfb8aa3b, v0
	v_exp_f32_e32 v56, v0
	v_mul_f32_e32 v0, 0x3d372713, v59
	v_mul_f32_e32 v0, v0, v59
	v_mov_b32_e32 v1, v59
	v_fmac_f32_e32 v1, v0, v1
	v_mul_f32_e32 v0, 0x3f4c422a, v1
	v_add_f32_e32 v0, v0, v0
	v_mul_f32_e32 v0, 0xbfb8aa3b, v0
	v_exp_f32_e32 v57, v0
	v_mfma_f32_16x16x32_bf16 v[0:3], v[92:95], v[80:83], v[62:65]
	v_add_f32_e64 v4, v36, v4
	v_add_f32_e64 v5, v36, v5
	v_pk_add_f32 v[6:7], v[36:37], v[6:7] op_sel_hi:[0,1]
	v_pk_add_f32 v[60:61], v[56:57], 1.0 op_sel_hi:[1,0]
	v_mad_i64_i32 v[56:57], s[0:1], v47, s86, v[32:33]
	v_mfma_f32_16x16x32_bf16 v[12:15], v[68:71], v[80:83], v[72:75]
	v_lshl_add_u64 v[56:57], v[56:57], 0, s[4:5]
	s_nop 0
	v_pk_add_f32 v[0:1], v[36:37], v[0:1] op_sel_hi:[0,1]
	v_rcp_f32_e32 v61, v61
	s_nop 3
	v_pk_add_f32 v[12:13], v[36:37], v[12:13] op_sel_hi:[0,1]
	v_lshlrev_b32_e32 v54, 16, v55
	v_mul_f32_e32 v62, 0x3d372713, v54
	v_mul_f32_e32 v62, v62, v54
	v_mov_b32_e32 v63, v54
	v_and_b32_e32 v55, 0xffff0000, v55
	v_fmac_f32_e32 v63, v62, v63
	v_mul_f32_e32 v62, 0x3f4c422a, v63
	v_mul_f32_e32 v63, 0x3d372713, v55
	v_mul_f32_e32 v63, v63, v55
	v_mov_b32_e32 v68, v55
	v_fmac_f32_e32 v68, v63, v68
	v_mul_f32_e32 v63, 0x3f4c422a, v68
	v_add_f32_e32 v62, v62, v62
	v_add_f32_e32 v63, v63, v63
	v_mul_f32_e32 v62, 0xbfb8aa3b, v62
	v_mul_f32_e32 v63, 0xbfb8aa3b, v63
	v_exp_f32_e32 v62, v62
	v_exp_f32_e32 v63, v63
	v_rcp_f32_e32 v60, v60
	s_nop 0
	v_pk_mul_f32 v[58:59], v[60:61], v[58:59]
	v_pk_add_f32 v[62:63], v[62:63], 1.0 op_sel_hi:[1,0]
	v_pk_add_f32 v[14:15], v[36:37], v[14:15] op_sel_hi:[0,1]
	v_pk_add_f32 v[60:61], v[46:47], v[84:85] op_sel_hi:[0,1]
	v_pk_mul_f32 v[58:59], v[58:59], v[60:61]
	v_pk_add_f32 v[2:3], v[36:37], v[2:3] op_sel_hi:[0,1]
	v_rcp_f32_e32 v61, v63
	v_cvt_pk_bf16_f32 v58, v58, v59
	v_rcp_f32_e32 v60, v62
	s_nop 0
	v_pk_mul_f32 v[54:55], v[60:61], v[54:55]
	v_lshlrev_b32_e32 v60, 16, v52
	v_mul_f32_e32 v47, 0x3d372713, v60
	v_and_b32_e32 v61, 0xffff0000, v52
	v_mul_f32_e32 v47, v47, v60
	v_mov_b32_e32 v52, v60
	v_fmac_f32_e32 v52, v47, v52
	v_mul_f32_e32 v47, 0x3f4c422a, v52
	v_add_f32_e32 v47, v47, v47
	v_mul_f32_e32 v47, 0xbfb8aa3b, v47
	v_exp_f32_e32 v62, v47
	v_mul_f32_e32 v47, 0x3d372713, v61
	v_mul_f32_e32 v47, v47, v61
	v_mov_b32_e32 v52, v61
	v_fmac_f32_e32 v52, v47, v52
	v_mul_f32_e32 v47, 0x3f4c422a, v52
	v_add_f32_e32 v47, v47, v47
	v_mul_f32_e32 v47, 0xbfb8aa3b, v47
	v_exp_f32_e32 v63, v47
	v_pk_add_f32 v[64:65], v[46:47], v[86:87] op_sel_hi:[0,1]
	v_pk_mul_f32 v[54:55], v[54:55], v[64:65]
	v_pk_add_f32 v[62:63], v[62:63], 1.0 op_sel_hi:[1,0]
	s_nop 0
	v_cvt_pk_bf16_f32 v59, v54, v55
	v_lshl_add_u64 v[54:55], v[56:57], 0, v[28:29]
	global_store_dwordx2 v[54:55], v[58:59], off
	v_rcp_f32_e32 v55, v63
	v_lshlrev_b32_e32 v52, 16, v53
	v_mul_f32_e32 v54, 0x3d372713, v52
	v_mul_f32_e32 v54, v54, v52
	v_mov_b32_e32 v58, v52
	v_fmac_f32_e32 v58, v54, v58
	v_mul_f32_e32 v54, 0x3f4c422a, v58
	v_add_f32_e32 v54, v54, v54
	v_and_b32_e32 v53, 0xffff0000, v53
	v_mul_f32_e32 v54, 0xbfb8aa3b, v54
	v_exp_f32_e32 v58, v54
	v_mul_f32_e32 v54, 0x3d372713, v53
	v_mul_f32_e32 v54, v54, v53
	v_mov_b32_e32 v59, v53
	v_fmac_f32_e32 v59, v54, v59
	v_mul_f32_e32 v54, 0x3f4c422a, v59
	v_add_f32_e32 v54, v54, v54
	v_mul_f32_e32 v54, 0xbfb8aa3b, v54
	v_exp_f32_e32 v59, v54
	v_rcp_f32_e32 v54, v62
	s_nop 0
	v_pk_mul_f32 v[54:55], v[54:55], v[60:61]
	v_pk_add_f32 v[58:59], v[58:59], 1.0 op_sel_hi:[1,0]
	s_nop 0
	v_pk_add_f32 v[24:25], v[46:47], v[24:25] op_sel_hi:[0,1]
	v_pk_mul_f32 v[24:25], v[54:55], v[24:25]
	v_rcp_f32_e32 v55, v59
	v_cvt_pk_bf16_f32 v24, v24, v25
	v_rcp_f32_e32 v54, v58
	s_nop 0
	v_pk_mul_f32 v[52:53], v[54:55], v[52:53]
	v_lshlrev_b32_e32 v54, 16, v50
	v_mul_f32_e32 v47, 0x3d372713, v54
	v_and_b32_e32 v55, 0xffff0000, v50
	v_mul_f32_e32 v47, v47, v54
	v_mov_b32_e32 v50, v54
	v_fmac_f32_e32 v50, v47, v50
	v_mul_f32_e32 v47, 0x3f4c422a, v50
	v_add_f32_e32 v47, v47, v47
	v_mul_f32_e32 v47, 0xbfb8aa3b, v47
	v_exp_f32_e32 v58, v47
	v_mul_f32_e32 v47, 0x3d372713, v55
	v_mul_f32_e32 v47, v47, v55
	v_mov_b32_e32 v50, v55
	v_fmac_f32_e32 v50, v47, v50
	v_mul_f32_e32 v47, 0x3f4c422a, v50
	v_add_f32_e32 v47, v47, v47
	v_mul_f32_e32 v47, 0xbfb8aa3b, v47
	v_exp_f32_e32 v59, v47
	v_pk_add_f32 v[26:27], v[46:47], v[26:27] op_sel_hi:[0,1]
	v_pk_mul_f32 v[26:27], v[52:53], v[26:27]
	v_pk_add_f32 v[52:53], v[58:59], 1.0 op_sel_hi:[1,0]
	s_nop 0
	v_cvt_pk_bf16_f32 v25, v26, v27
	v_lshl_add_u64 v[26:27], v[56:57], 0, v[30:31]
	global_store_dwordx2 v[26:27], v[24:25], off
	v_rcp_f32_e32 v25, v53
	v_lshlrev_b32_e32 v26, 16, v51
	v_mul_f32_e32 v50, 0x3d372713, v26
	v_and_b32_e32 v27, 0xffff0000, v51
	v_mul_f32_e32 v50, v50, v26
	v_mov_b32_e32 v51, v26
	v_fmac_f32_e32 v51, v50, v51
	v_mul_f32_e32 v50, 0x3f4c422a, v51
	v_mul_f32_e32 v51, 0x3d372713, v27
	v_mul_f32_e32 v51, v51, v27
	v_mov_b32_e32 v58, v27
	v_fmac_f32_e32 v58, v51, v58
	v_mul_f32_e32 v51, 0x3f4c422a, v58
	v_add_f32_e32 v50, v50, v50
	v_add_f32_e32 v51, v51, v51
	v_mul_f32_e32 v50, 0xbfb8aa3b, v50
	v_mul_f32_e32 v51, 0xbfb8aa3b, v51
	v_exp_f32_e32 v50, v50
	v_exp_f32_e32 v51, v51
	v_rcp_f32_e32 v24, v52
	s_nop 0
	v_pk_mul_f32 v[24:25], v[24:25], v[54:55]
	v_pk_add_f32 v[50:51], v[50:51], 1.0 op_sel_hi:[1,0]
	s_nop 0
	v_pk_add_f32 v[20:21], v[46:47], v[20:21] op_sel_hi:[0,1]
	v_pk_mul_f32 v[20:21], v[24:25], v[20:21]
	v_rcp_f32_e32 v25, v51
	v_cvt_pk_bf16_f32 v20, v20, v21
	v_rcp_f32_e32 v24, v50
	s_nop 0
	v_pk_mul_f32 v[24:25], v[24:25], v[26:27]
	v_lshlrev_b32_e32 v26, 16, v48
	v_mul_f32_e32 v47, 0x3d372713, v26
	v_and_b32_e32 v27, 0xffff0000, v48
	v_mul_f32_e32 v47, v47, v26
	v_mov_b32_e32 v48, v26
	v_fmac_f32_e32 v48, v47, v48
	v_mul_f32_e32 v47, 0x3f4c422a, v48
	v_add_f32_e32 v47, v47, v47
	v_mul_f32_e32 v47, 0xbfb8aa3b, v47
	v_exp_f32_e32 v50, v47
	v_mul_f32_e32 v47, 0x3d372713, v27
	v_mul_f32_e32 v47, v47, v27
	v_mov_b32_e32 v48, v27
	v_fmac_f32_e32 v48, v47, v48
	v_mul_f32_e32 v47, 0x3f4c422a, v48
	v_add_f32_e32 v47, v47, v47
	v_mul_f32_e32 v47, 0xbfb8aa3b, v47
	v_exp_f32_e32 v51, v47
	v_pk_add_f32 v[22:23], v[46:47], v[22:23] op_sel_hi:[0,1]
	v_pk_mul_f32 v[22:23], v[24:25], v[22:23]
	v_pk_add_f32 v[24:25], v[50:51], 1.0 op_sel_hi:[1,0]
	s_nop 0
	v_cvt_pk_bf16_f32 v21, v22, v23
	v_lshl_add_u64 v[22:23], v[56:57], 0, v[34:35]
	global_store_dwordx2 v[22:23], v[20:21], off
	v_rcp_f32_e32 v21, v25
	v_lshlrev_b32_e32 v22, 16, v49
	v_mul_f32_e32 v48, 0x3d372713, v22
	v_and_b32_e32 v23, 0xffff0000, v49
	v_mul_f32_e32 v48, v48, v22
	v_mov_b32_e32 v49, v22
	v_fmac_f32_e32 v49, v48, v49
	v_mul_f32_e32 v48, 0x3f4c422a, v49
	v_mul_f32_e32 v49, 0x3d372713, v23
	v_mul_f32_e32 v49, v49, v23
	v_mov_b32_e32 v50, v23
	v_fmac_f32_e32 v50, v49, v50
	v_mul_f32_e32 v49, 0x3f4c422a, v50
	v_add_f32_e32 v48, v48, v48
	v_add_f32_e32 v49, v49, v49
	v_mul_f32_e32 v48, 0xbfb8aa3b, v48
	v_mul_f32_e32 v49, 0xbfb8aa3b, v49
	v_exp_f32_e32 v48, v48
	v_exp_f32_e32 v49, v49
	v_rcp_f32_e32 v20, v24
	s_nop 0
	v_pk_mul_f32 v[20:21], v[20:21], v[26:27]
	v_pk_add_f32 v[24:25], v[48:49], 1.0 op_sel_hi:[1,0]
	s_nop 0
	v_pk_add_f32 v[16:17], v[46:47], v[16:17] op_sel_hi:[0,1]
	v_pk_mul_f32 v[16:17], v[20:21], v[16:17]
	v_rcp_f32_e32 v21, v25
	v_rcp_f32_e32 v20, v24
	s_nop 0
	v_pk_mul_f32 v[20:21], v[20:21], v[22:23]
	v_pk_add_f32 v[18:19], v[46:47], v[18:19] op_sel_hi:[0,1]
	v_pk_mul_f32 v[18:19], v[20:21], v[18:19]
	v_cvt_pk_bf16_f32 v16, v16, v17
	v_cvt_pk_bf16_f32 v17, v18, v19
	v_lshlrev_b32_e32 v18, 16, v44
	v_mul_f32_e32 v20, 0x3d372713, v18
	v_mul_f32_e32 v20, v20, v18
	v_mov_b32_e32 v21, v18
	v_and_b32_e32 v19, 0xffff0000, v44
	v_fmac_f32_e32 v21, v20, v21
	v_mul_f32_e32 v20, 0x3f4c422a, v21
	v_mul_f32_e32 v21, 0x3d372713, v19
	v_mul_f32_e32 v21, v21, v19
	v_mov_b32_e32 v22, v19
	v_fmac_f32_e32 v22, v21, v22
	v_mul_f32_e32 v21, 0x3f4c422a, v22
	v_add_f32_e32 v20, v20, v20
	v_add_f32_e32 v21, v21, v21
	v_mul_f32_e32 v20, 0xbfb8aa3b, v20
	v_mul_f32_e32 v21, 0xbfb8aa3b, v21
	v_exp_f32_e32 v20, v20
	v_exp_f32_e32 v21, v21
	v_lshl_add_u64 v[22:23], v[56:57], 0, v[66:67]
	global_store_dwordx2 v[22:23], v[16:17], off
	v_or_b32_e32 v16, s2, v37
	v_pk_add_f32 v[20:21], v[20:21], 1.0 op_sel_hi:[1,0]
	v_mad_i64_i32 v[16:17], s[0:1], v16, s86, v[32:33]
	v_lshl_add_u64 v[16:17], v[16:17], 0, s[4:5]
	v_rcp_f32_e32 v21, v21
	v_lshlrev_b32_e32 v22, 16, v45
	v_mul_f32_e32 v24, 0x3d372713, v22
	v_mul_f32_e32 v24, v24, v22
	v_mov_b32_e32 v25, v22
	v_and_b32_e32 v23, 0xffff0000, v45
	v_fmac_f32_e32 v25, v24, v25
	v_mul_f32_e32 v24, 0x3f4c422a, v25
	v_mul_f32_e32 v25, 0x3d372713, v23
	v_mul_f32_e32 v25, v25, v23
	v_mov_b32_e32 v33, v23
	v_fmac_f32_e32 v33, v25, v33
	v_mul_f32_e32 v25, 0x3f4c422a, v33
	v_add_f32_e32 v24, v24, v24
	v_add_f32_e32 v25, v25, v25
	v_mul_f32_e32 v24, 0xbfb8aa3b, v24
	v_mul_f32_e32 v25, 0xbfb8aa3b, v25
	v_exp_f32_e32 v24, v24
	v_exp_f32_e32 v25, v25
	v_rcp_f32_e32 v20, v20
	s_nop 0
	v_pk_mul_f32 v[18:19], v[20:21], v[18:19]
	v_pk_add_f32 v[24:25], v[24:25], 1.0 op_sel_hi:[1,0]
	v_pk_mul_f32 v[12:13], v[18:19], v[12:13]
	s_nop 0
	v_cvt_pk_bf16_f32 v12, v12, v13
	v_rcp_f32_e32 v19, v25
	v_rcp_f32_e32 v18, v24
	v_lshlrev_b32_e32 v20, 16, v42
	v_pk_mul_f32 v[18:19], v[18:19], v[22:23]
	v_mul_f32_e32 v22, 0x3d372713, v20
	v_mul_f32_e32 v22, v22, v20
	v_mov_b32_e32 v23, v20
	v_and_b32_e32 v21, 0xffff0000, v42
	v_fmac_f32_e32 v23, v22, v23
	v_mul_f32_e32 v22, 0x3f4c422a, v23
	v_mul_f32_e32 v23, 0x3d372713, v21
	v_mul_f32_e32 v23, v23, v21
	v_mov_b32_e32 v24, v21
	v_fmac_f32_e32 v24, v23, v24
	v_mul_f32_e32 v23, 0x3f4c422a, v24
	v_add_f32_e32 v22, v22, v22
	v_add_f32_e32 v23, v23, v23
	v_mul_f32_e32 v22, 0xbfb8aa3b, v22
	v_mul_f32_e32 v23, 0xbfb8aa3b, v23
	v_exp_f32_e32 v22, v22
	v_exp_f32_e32 v23, v23
	v_pk_mul_f32 v[14:15], v[18:19], v[14:15]
	v_pk_add_f32 v[18:19], v[22:23], 1.0 op_sel_hi:[1,0]
	s_nop 0
	v_cvt_pk_bf16_f32 v13, v14, v15
	v_lshl_add_u64 v[14:15], v[16:17], 0, v[28:29]
	global_store_dwordx2 v[14:15], v[12:13], off
	v_rcp_f32_e32 v13, v19
	v_lshlrev_b32_e32 v14, 16, v43
	v_mul_f32_e32 v22, 0x3d372713, v14
	v_mul_f32_e32 v22, v22, v14
	v_mov_b32_e32 v23, v14
	v_and_b32_e32 v15, 0xffff0000, v43
	v_fmac_f32_e32 v23, v22, v23
	v_mul_f32_e32 v22, 0x3f4c422a, v23
	v_mul_f32_e32 v23, 0x3d372713, v15
	v_mul_f32_e32 v23, v23, v15
	v_mov_b32_e32 v25, v15
	v_fmac_f32_e32 v25, v23, v25
	v_mul_f32_e32 v23, 0x3f4c422a, v25
	v_add_f32_e32 v22, v22, v22
	v_add_f32_e32 v23, v23, v23
	v_mul_f32_e32 v22, 0xbfb8aa3b, v22
	v_mul_f32_e32 v23, 0xbfb8aa3b, v23
	v_exp_f32_e32 v22, v22
	v_exp_f32_e32 v23, v23
	v_rcp_f32_e32 v12, v18
	s_nop 0
	v_pk_mul_f32 v[12:13], v[12:13], v[20:21]
	v_pk_add_f32 v[18:19], v[22:23], 1.0 op_sel_hi:[1,0]
	v_pk_mul_f32 v[8:9], v[12:13], v[8:9]
	s_nop 0
	v_cvt_pk_bf16_f32 v8, v8, v9
	v_rcp_f32_e32 v13, v19
	v_rcp_f32_e32 v12, v18
	s_nop 0
	v_pk_mul_f32 v[12:13], v[12:13], v[14:15]
	v_lshlrev_b32_e32 v14, 16, v40
	v_mul_f32_e32 v18, 0x3d372713, v14
	v_mul_f32_e32 v18, v18, v14
	v_mov_b32_e32 v19, v14
	v_and_b32_e32 v15, 0xffff0000, v40
	v_fmac_f32_e32 v19, v18, v19
	v_mul_f32_e32 v18, 0x3f4c422a, v19
	v_mul_f32_e32 v19, 0x3d372713, v15
	v_mul_f32_e32 v19, v19, v15
	v_mov_b32_e32 v20, v15
	v_fmac_f32_e32 v20, v19, v20
	v_mul_f32_e32 v19, 0x3f4c422a, v20
	v_add_f32_e32 v18, v18, v18
	v_add_f32_e32 v19, v19, v19
	v_mul_f32_e32 v18, 0xbfb8aa3b, v18
	v_mul_f32_e32 v19, 0xbfb8aa3b, v19
	v_exp_f32_e32 v18, v18
	v_exp_f32_e32 v19, v19
	v_pk_mul_f32 v[10:11], v[12:13], v[10:11]
	v_pk_add_f32 v[12:13], v[18:19], 1.0 op_sel_hi:[1,0]
	s_nop 0
	v_cvt_pk_bf16_f32 v9, v10, v11
	v_lshl_add_u64 v[10:11], v[16:17], 0, v[30:31]
	global_store_dwordx2 v[10:11], v[8:9], off
	v_rcp_f32_e32 v9, v13
	v_lshlrev_b32_e32 v10, 16, v41
	v_mul_f32_e32 v18, 0x3d372713, v10
	v_mul_f32_e32 v18, v18, v10
	v_mov_b32_e32 v19, v10
	v_and_b32_e32 v11, 0xffff0000, v41
	v_fmac_f32_e32 v19, v18, v19
	v_mul_f32_e32 v18, 0x3f4c422a, v19
	v_mul_f32_e32 v19, 0x3d372713, v11
	v_mul_f32_e32 v19, v19, v11
	v_mov_b32_e32 v21, v11
	v_fmac_f32_e32 v21, v19, v21
	v_mul_f32_e32 v19, 0x3f4c422a, v21
	v_add_f32_e32 v18, v18, v18
	v_add_f32_e32 v19, v19, v19
	v_mul_f32_e32 v18, 0xbfb8aa3b, v18
	v_mul_f32_e32 v19, 0xbfb8aa3b, v19
	v_exp_f32_e32 v18, v18
	v_exp_f32_e32 v19, v19
	v_rcp_f32_e32 v8, v12
	s_nop 0
	v_pk_mul_f32 v[8:9], v[8:9], v[14:15]
	v_pk_add_f32 v[12:13], v[18:19], 1.0 op_sel_hi:[1,0]
	v_pk_mul_f32 v[4:5], v[8:9], v[4:5]
	s_nop 0
	v_cvt_pk_bf16_f32 v4, v4, v5
	v_rcp_f32_e32 v9, v13
	v_rcp_f32_e32 v8, v12
	s_nop 0
	v_pk_mul_f32 v[8:9], v[8:9], v[10:11]
	v_lshlrev_b32_e32 v10, 16, v38
	v_mul_f32_e32 v12, 0x3d372713, v10
	v_mul_f32_e32 v12, v12, v10
	v_mov_b32_e32 v13, v10
	v_and_b32_e32 v11, 0xffff0000, v38
	v_fmac_f32_e32 v13, v12, v13
	v_mul_f32_e32 v12, 0x3f4c422a, v13
	v_mul_f32_e32 v13, 0x3d372713, v11
	v_mul_f32_e32 v13, v13, v11
	v_mov_b32_e32 v14, v11
	v_fmac_f32_e32 v14, v13, v14
	v_mul_f32_e32 v13, 0x3f4c422a, v14
	v_add_f32_e32 v12, v12, v12
	v_add_f32_e32 v13, v13, v13
	v_mul_f32_e32 v12, 0xbfb8aa3b, v12
	v_mul_f32_e32 v13, 0xbfb8aa3b, v13
	v_exp_f32_e32 v12, v12
	v_exp_f32_e32 v13, v13
	v_pk_mul_f32 v[6:7], v[8:9], v[6:7]
	v_pk_add_f32 v[8:9], v[12:13], 1.0 op_sel_hi:[1,0]
	s_nop 0
	v_cvt_pk_bf16_f32 v5, v6, v7
	v_lshl_add_u64 v[6:7], v[16:17], 0, v[34:35]
	global_store_dwordx2 v[6:7], v[4:5], off
	v_rcp_f32_e32 v5, v9
	v_lshlrev_b32_e32 v6, 16, v39
	v_mul_f32_e32 v12, 0x3d372713, v6
	v_mul_f32_e32 v12, v12, v6
	v_mov_b32_e32 v13, v6
	v_and_b32_e32 v7, 0xffff0000, v39
	v_fmac_f32_e32 v13, v12, v13
	v_mul_f32_e32 v12, 0x3f4c422a, v13
	v_mul_f32_e32 v13, 0x3d372713, v7
	v_mul_f32_e32 v13, v13, v7
	v_mov_b32_e32 v15, v7
	v_fmac_f32_e32 v15, v13, v15
	v_mul_f32_e32 v13, 0x3f4c422a, v15
	v_add_f32_e32 v12, v12, v12
	v_add_f32_e32 v13, v13, v13
	v_mul_f32_e32 v12, 0xbfb8aa3b, v12
	v_mul_f32_e32 v13, 0xbfb8aa3b, v13
	v_exp_f32_e32 v12, v12
	v_exp_f32_e32 v13, v13
	v_rcp_f32_e32 v4, v8
	s_nop 0
	v_pk_mul_f32 v[4:5], v[4:5], v[10:11]
	v_pk_add_f32 v[8:9], v[12:13], 1.0 op_sel_hi:[1,0]
	v_pk_mul_f32 v[0:1], v[4:5], v[0:1]
	s_nop 0
	v_cvt_pk_bf16_f32 v0, v0, v1
	v_rcp_f32_e32 v5, v9
	v_rcp_f32_e32 v4, v8
	s_nop 0
	v_pk_mul_f32 v[4:5], v[4:5], v[6:7]
	s_nop 0
	v_pk_mul_f32 v[2:3], v[4:5], v[2:3]
	s_nop 0
	v_cvt_pk_bf16_f32 v1, v2, v3
	v_lshl_add_u64 v[2:3], v[16:17], 0, v[66:67]
	global_store_dwordx2 v[2:3], v[0:1], off
	s_waitcnt lgkmcnt(0)
	s_barrier
	s_cmp_lt_u32 s100, 0x7c
	s_cbranch_scc1 .Lgmlp_done
	s_cmp_lg_u32 s101, 0
	s_cbranch_scc1 .Lgmlp_restore
	s_mov_b32 s101, 1
	s_sub_i32 s2, s100, 0x7c
	s_lshl_b32 s2, s2, 7
	s_add_i32 s65, s2, 0x4000
	v_writelane_b32 v253, s2, 36
	s_branch .Lgmlp_again
.Lgmlp_restore:
	s_lshl_b32 s2, s100, 7
	s_add_i32 s65, s2, 0x4000
	v_writelane_b32 v253, s2, 36
.Lgmlp_done:
.LBB0_605:
	s_waitcnt vmcnt(0) lgkmcnt(0)
	v_add_u32_e32 v41, 3, v245
	s_waitcnt vmcnt(0) lgkmcnt(0)
	s_barrier
	s_and_saveexec_b64 s[0:1], s[90:91]
	s_xor_b64 s[0:1], exec, s[0:1]
	v_add_u32_e32 v41, 3, v245
	s_or_saveexec_b64 s[0:1], s[0:1]
	v_readlane_b32 s97, v255, 27
	s_xor_b64 exec, exec, s[0:1]
	s_cbranch_execz .LBB0_667
	s_mov_b64 s[4:5], exec
	v_mbcnt_lo_u32_b32 v0, s4, 0
	v_mbcnt_hi_u32_b32 v0, s5, v0
	v_cmp_eq_u32_e32 vcc, 0, v0
	s_and_saveexec_b64 s[2:3], vcc
	s_cbranch_execz .LBB0_610
	s_bcnt1_i32_b64 s4, s[4:5]
	v_mov_b32_e32 v1, s4
	v_readlane_b32 s4, v253, 14
	v_readlane_b32 s5, v253, 15
	s_nop 4
	global_atomic_add v1, v195, v1, s[4:5] sc0

	.amdhsa_kernel _Z10hybrid_fwd6Params
		.amdhsa_group_segment_fixed_size 8192
		.amdhsa_private_segment_fixed_size 0
		.amdhsa_kernarg_size 600
		.amdhsa_user_sgpr_count 2
		.amdhsa_user_sgpr_dispatch_ptr 0
		.amdhsa_user_sgpr_queue_ptr 0
		.amdhsa_user_sgpr_kernarg_segment_ptr 1
		.amdhsa_user_sgpr_dispatch_id 0
		.amdhsa_user_sgpr_kernarg_preload_length 0
		.amdhsa_user_sgpr_kernarg_preload_offset 0
		.amdhsa_user_sgpr_private_segment_size 0
		.amdhsa_uses_dynamic_stack 0
		.amdhsa_enable_private_segment 0
		.amdhsa_system_sgpr_workgroup_id_x 1
		.amdhsa_system_sgpr_workgroup_id_y 0
		.amdhsa_system_sgpr_workgroup_id_z 0
		.amdhsa_system_sgpr_workgroup_info 0
		.amdhsa_system_vgpr_workitem_id 2
		.amdhsa_next_free_vgpr 256
		.amdhsa_next_free_sgpr 102
		.amdhsa_accum_offset 256
		.amdhsa_reserve_vcc 1
		.amdhsa_float_round_mode_32 0
		.amdhsa_float_round_mode_16_64 0
		.amdhsa_float_denorm_mode_32 3
		.amdhsa_float_denorm_mode_16_64 3
		.amdhsa_dx10_clamp 1
		.amdhsa_ieee_mode 1
		.amdhsa_fp16_overflow 0
		.amdhsa_tg_split 0
		.amdhsa_exception_fp_ieee_invalid_op 0
		.amdhsa_exception_fp_denorm_src 0
		.amdhsa_exception_fp_ieee_div_zero 0
		.amdhsa_exception_fp_ieee_overflow 0
		.amdhsa_exception_fp_ieee_underflow 0
		.amdhsa_exception_fp_ieee_inexact 0
		.amdhsa_exception_int_div_zero 0
	.end_amdhsa_kernel

amdhsa.kernels:
  - .agpr_count:     0
    .args:
      - .offset:         0
        .size:           344
        .value_kind:     by_value
      - .offset:         344
        .size:           4
        .value_kind:     hidden_block_count_x
      - .offset:         348
        .size:           4
        .value_kind:     hidden_block_count_y
      - .offset:         352
        .size:           4
        .value_kind:     hidden_block_count_z
      - .offset:         356
        .size:           2
        .value_kind:     hidden_group_size_x
      - .offset:         358
        .size:           2
        .value_kind:     hidden_group_size_y
      - .offset:         360
        .size:           2
        .value_kind:     hidden_group_size_z
      - .offset:         362
        .size:           2
        .value_kind:     hidden_remainder_x
      - .offset:         364
        .size:           2
        .value_kind:     hidden_remainder_y
      - .offset:         366
        .size:           2
        .value_kind:     hidden_remainder_z
      - .offset:         384
        .size:           8
        .value_kind:     hidden_global_offset_x
      - .offset:         392
        .size:           8
        .value_kind:     hidden_global_offset_y
      - .offset:         400
        .size:           8
        .value_kind:     hidden_global_offset_z
      - .offset:         408
        .size:           2
        .value_kind:     hidden_grid_dims
      - .offset:         432
        .size:           8
        .value_kind:     hidden_multigrid_sync_arg
      - .offset:         464
        .size:           4
        .value_kind:     hidden_dynamic_lds_size
    .group_segment_fixed_size: 8192
    .kernarg_segment_align: 8
    .kernarg_segment_size: 600
    .language:       OpenCL C
    .language_version:
      - 2
      - 0
    .max_flat_workgroup_size: 512
    .name:           _Z10hybrid_fwd6Params
    .private_segment_fixed_size: 0
    .sgpr_count:     108
    .sgpr_spill_count: 263
    .symbol:         _Z10hybrid_fwd6Params.kd
    .uniform_work_group_size: 1
    .uses_dynamic_stack: false
    .vgpr_count:     256
    .vgpr_spill_count: 0
    .wavefront_size: 64
